# RG-LRU gate column loads issued before the segment scan instead of after it
# baseline (speedup 1.0000x reference)
; __device__ __forceinline__ float bf2f(unsigned v) { return __uint_as_float(v << 16); }
; __device__ __forceinline__ void rg_item(CArgs& A, int l, const bf16* P, bf16* Y, int b, int h, int cg, float* ldsf, int tid) {
;     ...
;         __syncthreads();
;         float aa[16], uu[16];
;         {
;             float Ap = 1.f, hl = 0.f;
; #pragma unroll
;             for (int j = 0; j < 16; ++j) { aa[j] = a_s[(seg * 16 + j) * 16 + c]; uu[j] = u_s[(seg * 16 + j) * 16 + c]; hl = aa[j] * hl + uu[j]; Ap *= aa[j]; }
;             segA[seg * 16 + c] = Ap; segH[seg * 16 + c] = hl;
;         }
;         __syncthreads();
;         float hv = carry[c];
;         for (int sgm = 0; sgm < seg; ++sgm) hv = segA[sgm * 16 + c] * hv + segH[sgm * 16 + c];
;         {
;             const size_t row0 = (size_t)b * SEQ + qtr * 512 + seg * 16;
;             float gate[16];
; #pragma unroll
;             for (int j = 0; j < 16; ++j) gate[j] = bf2f(P[(row0 + j) * NP + PC_RGG + h * 64 + cg * 16 + c]);
.LBB0_363:
	s_or_b64 exec, exec, s[64:65]
	s_lshl_b32 s14, s87, 9
	v_lshl_add_u64 v[226:227], v[80:81], 0, s[14:15]
	v_mov_b64_e32 v[228:229], s[38:39]
	v_mad_u64_u32 v[228:229], s[0:1], v226, s79, v[228:229]
	v_mad_i32_i24 v229, v227, s79, v229
	s_mov_b32 s55, s15
	v_lshl_add_u64 v[228:229], v[228:229], 0, s[54:55]
	s_mov_b32 s63, s15
	v_lshl_add_u64 v[228:229], v[228:229], 0, s[62:63]
	v_mov_b32_e32 v85, v0
	v_lshl_add_u64 v[228:229], v[228:229], 0, v[84:85]
	global_load_ushort v210, v[228:229], off offset:512
	s_mov_b64 s[100:101], 0x1000
	v_lshl_add_u64 v[226:227], v[228:229], 0, s[100:101]
	global_load_ushort v211, v[226:227], off offset:2048
	s_mov_b64 s[100:101], 0x2000
	v_lshl_add_u64 v[226:227], v[228:229], 0, s[100:101]
	global_load_ushort v212, v[226:227], off offset:3584
	s_mov_b64 s[100:101], 0x4000
	v_lshl_add_u64 v[226:227], v[228:229], 0, s[100:101]
	global_load_ushort v213, v[226:227], off offset:1024
	s_mov_b64 s[100:101], 0x5000
	v_lshl_add_u64 v[226:227], v[228:229], 0, s[100:101]
	global_load_ushort v214, v[226:227], off offset:2560
	s_mov_b64 s[100:101], 0x7000
	v_lshl_add_u64 v[226:227], v[228:229], 0, s[100:101]
	global_load_ushort v215, v[226:227], off
	s_mov_b64 s[100:101], 0x8000
	v_lshl_add_u64 v[226:227], v[228:229], 0, s[100:101]
	global_load_ushort v216, v[226:227], off offset:1536
	s_mov_b64 s[100:101], 0x9000
	v_lshl_add_u64 v[226:227], v[228:229], 0, s[100:101]
	global_load_ushort v217, v[226:227], off offset:3072
	s_mov_b64 s[100:101], 0xb000
	v_lshl_add_u64 v[226:227], v[228:229], 0, s[100:101]
	global_load_ushort v218, v[226:227], off offset:512
	s_mov_b64 s[100:101], 0xc000
	v_lshl_add_u64 v[226:227], v[228:229], 0, s[100:101]
	global_load_ushort v219, v[226:227], off offset:2048
	s_mov_b64 s[100:101], 0xd000
	v_lshl_add_u64 v[226:227], v[228:229], 0, s[100:101]
	global_load_ushort v220, v[226:227], off offset:3584
	s_mov_b64 s[100:101], 0xf000
	v_lshl_add_u64 v[226:227], v[228:229], 0, s[100:101]
	global_load_ushort v221, v[226:227], off offset:1024
	s_mov_b64 s[100:101], 0x10000
	v_lshl_add_u64 v[226:227], v[228:229], 0, s[100:101]
	global_load_ushort v222, v[226:227], off offset:2560
	s_mov_b64 s[100:101], 0x12000
	v_lshl_add_u64 v[226:227], v[228:229], 0, s[100:101]
	global_load_ushort v223, v[226:227], off
	s_mov_b64 s[100:101], 0x13000
	v_lshl_add_u64 v[226:227], v[228:229], 0, s[100:101]
	global_load_ushort v224, v[226:227], off offset:1536
	s_mov_b64 s[100:101], 0x14000
	v_lshl_add_u64 v[226:227], v[228:229], 0, s[100:101]
	global_load_ushort v225, v[226:227], off offset:3072
	v_add_u32_e32 v2, 0x1400, v91
	v_add_u32_e32 v3, 0x9400, v91
	s_waitcnt lgkmcnt(0)
	s_barrier
	ds_read2_b32 v[48:49], v2 offset0:128 offset1:144
	ds_read2_b32 v[46:47], v3 offset0:128 offset1:144
	ds_read2_b32 v[44:45], v2 offset0:160 offset1:176
	ds_read2_b32 v[42:43], v3 offset0:160 offset1:176
	ds_read2_b32 v[40:41], v2 offset0:192 offset1:208
	ds_read2_b32 v[38:39], v3 offset0:192 offset1:208
	ds_read2_b32 v[36:37], v2 offset0:224 offset1:240
	ds_read2_b32 v[34:35], v3 offset0:224 offset1:240
	s_waitcnt lgkmcnt(7)
	v_mul_f32_e32 v5, v48, v49
	s_waitcnt lgkmcnt(6)
	v_fma_f32 v4, 0, v48, v46
	v_fma_f32 v4, v4, v49, v47
	s_waitcnt lgkmcnt(4)
	v_fma_f32 v4, v4, v44, v42
	v_mul_f32_e32 v5, v5, v44
	v_add_u32_e32 v2, 0x1800, v91
	v_add_u32_e32 v3, 0x9800, v91
	v_fma_f32 v4, v4, v45, v43
	v_mul_f32_e32 v5, v5, v45
	ds_read2_b32 v[16:17], v2 offset1:16
	ds_read2_b32 v[14:15], v3 offset1:16
	s_waitcnt lgkmcnt(4)
	v_fma_f32 v4, v4, v40, v38
	v_mul_f32_e32 v5, v5, v40
	v_fma_f32 v4, v4, v41, v39
	v_mul_f32_e32 v5, v5, v41
	s_waitcnt lgkmcnt(2)
	v_fma_f32 v4, v4, v36, v34
	v_mul_f32_e32 v5, v5, v36
	v_fma_f32 v4, v4, v37, v35
	v_mul_f32_e32 v5, v5, v37
	ds_read2_b32 v[10:11], v2 offset0:32 offset1:48
	ds_read2_b32 v[8:9], v3 offset0:32 offset1:48
	s_waitcnt lgkmcnt(2)
	v_fma_f32 v4, v4, v16, v14
	v_mul_f32_e32 v5, v5, v16
	v_fma_f32 v12, v4, v17, v15
	v_mul_f32_e32 v13, v5, v17
	ds_read2_b32 v[6:7], v2 offset0:64 offset1:80
	ds_read2_b32 v[4:5], v3 offset0:64 offset1:80
	s_waitcnt lgkmcnt(2)
	v_fma_f32 v2, v12, v10, v8
	v_mul_f32_e32 v3, v13, v10
	v_fma_f32 v2, v2, v11, v9
	v_mul_f32_e32 v3, v3, v11
	ds_read_b32 v51, v91 offset:6528
	ds_read_b32 v50, v91 offset:39296
	s_waitcnt lgkmcnt(2)
	v_fma_f32 v12, v2, v6, v4
	v_mul_f32_e32 v13, v3, v6
	ds_read2st64_b32 v[2:3], v92 offset0:22 offset1:150
	v_fma_f32 v12, v12, v7, v5
	v_mul_f32_e32 v13, v13, v7
	s_waitcnt lgkmcnt(1)
	v_fma_f32 v12, v12, v51, v50
	v_mul_f32_e32 v13, v13, v51
	s_waitcnt lgkmcnt(0)
	v_fma_f32 v12, v12, v2, v3
	v_mul_f32_e32 v13, v13, v2
	ds_write2st64_b32 v1, v13, v12 offset0:6 offset1:14
	s_waitcnt lgkmcnt(0)
	s_barrier
	ds_read_b32 v65, v90 offset:1472
	s_and_saveexec_b64 s[4:5], s[42:43]
	s_cbranch_execz .LBB0_367
	s_mov_b64 s[10:11], 0
	v_mov_b32_e32 v12, v96
	v_mov_b32_e32 v13, v88

; __device__ __forceinline__ float bf2f(unsigned v) { return __uint_as_float(v << 16); }
; __device__ __forceinline__ unsigned f2bf(float f) { unsigned u = __float_as_uint(f); return (u + 0x7fffu + ((u >> 16) & 1u)) >> 16; }
; __device__ __forceinline__ float gelu_tanh(float x) { return 0.5f * x * (1.f + tanhf(0.7978845608028654f * (x + 0.044715f * x * x * x))); }
; __device__ __forceinline__ void rg_item(CArgs& A, int l, const bf16* P, bf16* Y, int b, int h, int cg, float* ldsf, int tid) {
;     ...
;             const size_t row0 = (size_t)b * SEQ + qtr * 512 + seg * 16;
;             float gate[16];
; #pragma unroll
;             for (int j = 0; j < 16; ++j) gate[j] = bf2f(P[(row0 + j) * NP + PC_RGG + h * 64 + cg * 16 + c]);
; #pragma unroll
;             for (int j = 0; j < 16; ++j) { hv = aa[j] * hv + uu[j]; Y[(row0 + j) * DM + h * 64 + cg * 16 + c] = (bf16)f2bf(hv * gelu_tanh(gate[j])); }
.LBB0_367:
	s_or_b64 exec, exec, s[4:5]
	s_lshl_b32 s14, s87, 9
	v_lshl_add_u64 v[12:13], v[80:81], 0, s[14:15]
	v_mov_b64_e32 v[52:53], s[38:39]
	v_mad_u64_u32 v[52:53], s[0:1], v12, s79, v[52:53]
	v_mad_i32_i24 v53, v13, s79, v53
	s_mov_b32 s55, s15
	v_lshl_add_u64 v[52:53], v[52:53], 0, s[54:55]
	s_mov_b32 s63, s15
	v_lshl_add_u64 v[52:53], v[52:53], 0, s[62:63]
	v_mov_b32_e32 v85, v0
	v_lshl_add_u64 v[70:71], v[52:53], 0, v[84:85]
	s_movk_i32 s0, 0x4000
	s_waitcnt vmcnt(15)
	v_lshlrev_b32_e32 v67, 16, v210
	v_add_co_u32_e32 v52, vcc, s85, v70
	v_mul_f32_e32 v69, 0x3d372713, v67
	s_nop 0
	v_addc_co_u32_e32 v53, vcc, 0, v71, vcc
	v_add_co_u32_e32 v52, vcc, s33, v70
	v_mul_f32_e32 v69, v69, v67
	s_nop 0
	v_addc_co_u32_e32 v53, vcc, 0, v71, vcc
	v_add_co_u32_e32 v52, vcc, s0, v70
	s_movk_i32 s0, 0x5000
	s_nop 0
	v_addc_co_u32_e32 v53, vcc, 0, v71, vcc
	v_add_co_u32_e32 v52, vcc, s0, v70
	s_movk_i32 s0, 0x7000
	s_nop 0
	v_addc_co_u32_e32 v53, vcc, 0, v71, vcc
	v_add_co_u32_e32 v52, vcc, s0, v70
	s_mov_b32 s0, 0xb000
	s_nop 0
	v_addc_co_u32_e32 v53, vcc, 0, v71, vcc
	v_add_co_u32_e32 v52, vcc, s19, v70
	v_fma_f32 v69, v69, v67, v67
	s_nop 0
	v_addc_co_u32_e32 v53, vcc, 0, v71, vcc
	v_add_co_u32_e32 v52, vcc, s12, v70
	v_mul_f32_e32 v69, 0x3f4c422a, v69
	s_nop 0
	v_addc_co_u32_e32 v53, vcc, 0, v71, vcc
	v_add_co_u32_e32 v52, vcc, s0, v70
	s_mov_b32 s0, 0xc000
	s_nop 0
	v_addc_co_u32_e32 v53, vcc, 0, v71, vcc
	v_add_co_u32_e32 v52, vcc, s0, v70
	s_mov_b32 s0, 0xd000
	s_nop 0
	v_addc_co_u32_e32 v53, vcc, 0, v71, vcc
	v_add_co_u32_e32 v52, vcc, s0, v70
	s_mov_b32 s0, 0xf000
	s_nop 0
	v_addc_co_u32_e32 v53, vcc, 0, v71, vcc
	v_add_co_u32_e32 v52, vcc, s0, v70
	s_mov_b32 s0, 0x12000
	s_nop 0
	v_addc_co_u32_e32 v53, vcc, 0, v71, vcc
	v_add_co_u32_e32 v52, vcc, s13, v70
	s_nop 1
	v_addc_co_u32_e32 v53, vcc, 0, v71, vcc
	v_add_co_u32_e32 v52, vcc, s0, v70
	v_cmp_nlt_f32_e64 s[0:1], |v69|, s80
	s_nop 0
	v_addc_co_u32_e32 v53, vcc, 0, v71, vcc
	v_add_co_u32_e32 v52, vcc, 0x13000, v70
	s_nop 1
	v_addc_co_u32_e32 v53, vcc, 0, v71, vcc
	v_add_co_u32_e32 v70, vcc, 0x14000, v70
	s_nop 0
	v_addc_co_u32_e32 v71, vcc, 0, v71, vcc
	s_and_saveexec_b64 s[4:5], s[0:1]
	s_xor_b64 s[4:5], exec, s[4:5]
	s_cbranch_execz .LBB0_369
	v_add_f32_e64 v70, |v69|, |v69|
	v_mul_f32_e32 v71, 0x3fb8aa3b, v70
	v_rndne_f32_e32 v72, v71
	v_sub_f32_e32 v73, v71, v72
	v_fma_f32 v71, v70, s83, -v71
	v_fmac_f32_e32 v71, 0x32a5705f, v70
	v_add_f32_e32 v71, v73, v71
	v_cvt_i32_f32_e32 v72, v72
	v_exp_f32_e32 v71, v71
	v_cmp_ngt_f32_e32 vcc, s76, v70
	v_ldexp_f32 v71, v71, v72
	s_nop 0
	v_cndmask_b32_e32 v71, 0, v71, vcc
	v_cmp_nlt_f32_e32 vcc, s77, v70
	s_nop 1
	v_cndmask_b32_e32 v70, v181, v71, vcc
	v_add_f32_e32 v70, 1.0, v70
	v_rcp_f32_e32 v70, v70
	s_nop 0
	v_fma_f32 v70, v70, -2.0, 1.0
.LBB0_369:
	s_andn2_saveexec_b64 s[4:5], s[4:5]
	v_mul_f32_e32 v70, v69, v69
	v_fmamk_f32 v71, v70, 0xbbbac73d, v170
	v_fmaak_f32 v71, v70, v71, 0xbd5c1c4e
	v_fmaak_f32 v71, v70, v71, 0x3e088382
	v_fmaak_f32 v71, v70, v71, 0xbeaaaa99
	v_mul_f32_e64 v71, |v69|, v71
	v_fma_f32 v70, v70, v71, |v69|
	s_or_b64 exec, exec, s[4:5]
	s_waitcnt lgkmcnt(0)
	v_fma_f32 v46, v48, v65, v46
	v_bfi_b32 v65, s2, v70, v69
	v_mul_f32_e32 v48, 0.5, v67
	v_add_f32_e32 v65, 1.0, v65
	v_mul_f32_e32 v48, v48, v65
	v_mul_f32_e32 v48, v46, v48
	v_bfe_u32 v65, v48, 16, 1
	v_lshlrev_b64 v[12:13], 11, v[12:13]
	s_waitcnt vmcnt(14)
	v_lshlrev_b32_e32 v68, 16, v211
	v_add3_u32 v48, v48, v65, s84
	v_lshl_add_u64 v[70:71], v[82:83], 0, v[12:13]
	global_store_short_d16_hi v[70:71], v48, off
	v_mul_f32_e32 v48, 0x3d372713, v68
	v_mul_f32_e32 v48, v48, v68
	v_fma_f32 v48, v48, v68, v68
	v_mul_f32_e32 v48, 0x3f4c422a, v48
	v_cmp_nlt_f32_e64 s[0:1], |v48|, s80
	s_and_saveexec_b64 s[4:5], s[0:1]
	s_xor_b64 s[4:5], exec, s[4:5]
	s_cbranch_execz .LBB0_373
	v_add_f32_e64 v65, |v48|, |v48|
	v_mul_f32_e32 v67, 0x3fb8aa3b, v65
	v_rndne_f32_e32 v69, v67
	v_sub_f32_e32 v70, v67, v69
	v_fma_f32 v67, v65, s83, -v67
	v_fmac_f32_e32 v67, 0x32a5705f, v65
	v_add_f32_e32 v67, v70, v67
	v_cvt_i32_f32_e32 v69, v69
	v_exp_f32_e32 v67, v67
	v_cmp_ngt_f32_e32 vcc, s76, v65
	v_ldexp_f32 v67, v67, v69
	s_nop 0
	v_cndmask_b32_e32 v67, 0, v67, vcc
	v_cmp_nlt_f32_e32 vcc, s77, v65
	s_nop 1
	v_cndmask_b32_e32 v65, v181, v67, vcc
	v_add_f32_e32 v65, 1.0, v65
	v_rcp_f32_e32 v65, v65
	s_nop 0
	v_fma_f32 v65, v65, -2.0, 1.0
.LBB0_373:
	s_andn2_saveexec_b64 s[4:5], s[4:5]
	v_mul_f32_e32 v65, v48, v48
	v_fmamk_f32 v67, v65, 0xbbbac73d, v170
	v_fmaak_f32 v67, v65, v67, 0xbd5c1c4e
	v_fmaak_f32 v67, v65, v67, 0x3e088382
	v_fmaak_f32 v67, v65, v67, 0xbeaaaa99
	v_mul_f32_e64 v67, |v48|, v67
	v_fma_f32 v65, v65, v67, |v48|
	s_or_b64 exec, exec, s[4:5]
	v_bfi_b32 v48, s2, v65, v48
	v_fmac_f32_e32 v47, v49, v46
	v_mul_f32_e32 v49, 0.5, v68
	v_add_f32_e32 v48, 1.0, v48
	v_mul_f32_e32 v48, v49, v48
	v_mul_f32_e32 v48, v47, v48
	v_bfe_u32 v49, v48, 16, 1
	v_add3_u32 v65, v48, v49, s84
	v_or_b32_e32 v48, 0x800, v12
	v_mov_b32_e32 v49, v13
	s_waitcnt vmcnt(14)
	v_lshlrev_b32_e32 v46, 16, v212
	v_lshl_add_u64 v[48:49], v[82:83], 0, v[48:49]
	global_store_short_d16_hi v[48:49], v65, off
	v_mul_f32_e32 v48, 0x3d372713, v46
	v_mul_f32_e32 v48, v48, v46
	v_fma_f32 v48, v48, v46, v46
	v_mul_f32_e32 v48, 0x3f4c422a, v48
	v_cmp_nlt_f32_e64 s[0:1], |v48|, s80
	s_and_saveexec_b64 s[4:5], s[0:1]
	s_xor_b64 s[4:5], exec, s[4:5]
	s_cbranch_execz .LBB0_377
	v_add_f32_e64 v49, |v48|, |v48|
	v_mul_f32_e32 v65, 0x3fb8aa3b, v49
	v_rndne_f32_e32 v66, v65
	v_sub_f32_e32 v67, v65, v66
	v_fma_f32 v65, v49, s83, -v65
	v_fmac_f32_e32 v65, 0x32a5705f, v49
	v_add_f32_e32 v65, v67, v65
	v_cvt_i32_f32_e32 v66, v66
	v_exp_f32_e32 v65, v65
	v_cmp_ngt_f32_e32 vcc, s76, v49
	v_ldexp_f32 v65, v65, v66
	s_nop 0
	v_cndmask_b32_e32 v65, 0, v65, vcc
	v_cmp_nlt_f32_e32 vcc, s77, v49
	s_nop 1
	v_cndmask_b32_e32 v49, v181, v65, vcc
	v_add_f32_e32 v49, 1.0, v49
	v_rcp_f32_e32 v49, v49
	s_nop 0
	v_fma_f32 v49, v49, -2.0, 1.0
; __device__ __forceinline__ float bf2f(unsigned v) { return __uint_as_float(v << 16); }
; __device__ __forceinline__ unsigned f2bf(float f) { unsigned u = __float_as_uint(f); return (u + 0x7fffu + ((u >> 16) & 1u)) >> 16; }
; __device__ __forceinline__ float gelu_tanh(float x) { return 0.5f * x * (1.f + tanhf(0.7978845608028654f * (x + 0.044715f * x * x * x))); }
; __device__ __forceinline__ void rg_item(CArgs& A, int l, const bf16* P, bf16* Y, int b, int h, int cg, float* ldsf, int tid) {
;     ...
;             for (int j = 0; j < 16; ++j) gate[j] = bf2f(P[(row0 + j) * NP + PC_RGG + h * 64 + cg * 16 + c]);
; #pragma unroll
;             for (int j = 0; j < 16; ++j) { hv = aa[j] * hv + uu[j]; Y[(row0 + j) * DM + h * 64 + cg * 16 + c] = (bf16)f2bf(hv * gelu_tanh(gate[j])); }
.LBB0_377:
	s_andn2_saveexec_b64 s[4:5], s[4:5]
	v_mul_f32_e32 v49, v48, v48
	v_fmamk_f32 v65, v49, 0xbbbac73d, v170
	v_fmaak_f32 v65, v49, v65, 0xbd5c1c4e
	v_fmaak_f32 v65, v49, v65, 0x3e088382
	v_fmaak_f32 v65, v49, v65, 0xbeaaaa99
	v_mul_f32_e64 v65, |v48|, v65
	v_fma_f32 v49, v49, v65, |v48|
	s_or_b64 exec, exec, s[4:5]
	v_fma_f32 v44, v44, v47, v42
	v_bfi_b32 v47, s2, v49, v48
	v_mul_f32_e32 v46, 0.5, v46
	v_add_f32_e32 v47, 1.0, v47
	v_mul_f32_e32 v46, v46, v47
	v_mul_f32_e32 v46, v44, v46
	v_bfe_u32 v47, v46, 16, 1
	v_add3_u32 v48, v46, v47, s84
	v_or_b32_e32 v46, 0x1000, v12
	v_mov_b32_e32 v47, v13
	s_waitcnt vmcnt(14)
	v_lshlrev_b32_e32 v42, 16, v213
	v_lshl_add_u64 v[46:47], v[82:83], 0, v[46:47]
	global_store_short_d16_hi v[46:47], v48, off
	v_mul_f32_e32 v46, 0x3d372713, v42
	v_mul_f32_e32 v46, v46, v42
	v_fma_f32 v46, v46, v42, v42
	v_mul_f32_e32 v46, 0x3f4c422a, v46
	v_cmp_nlt_f32_e64 s[0:1], |v46|, s80
	s_and_saveexec_b64 s[4:5], s[0:1]
	s_xor_b64 s[4:5], exec, s[4:5]
	s_cbranch_execz .LBB0_381
	v_add_f32_e64 v47, |v46|, |v46|
	v_mul_f32_e32 v48, 0x3fb8aa3b, v47
	v_rndne_f32_e32 v49, v48
	v_sub_f32_e32 v64, v48, v49
	v_fma_f32 v48, v47, s83, -v48
	v_fmac_f32_e32 v48, 0x32a5705f, v47
	v_add_f32_e32 v48, v64, v48
	v_cvt_i32_f32_e32 v49, v49
	v_exp_f32_e32 v48, v48
	v_cmp_ngt_f32_e32 vcc, s76, v47
	v_ldexp_f32 v48, v48, v49
	s_nop 0
	v_cndmask_b32_e32 v48, 0, v48, vcc
	v_cmp_nlt_f32_e32 vcc, s77, v47
	s_nop 1
	v_cndmask_b32_e32 v47, v181, v48, vcc
	v_add_f32_e32 v47, 1.0, v47
	v_rcp_f32_e32 v47, v47
	s_nop 0
	v_fma_f32 v47, v47, -2.0, 1.0
.LBB0_381:
	s_andn2_saveexec_b64 s[4:5], s[4:5]
	v_mul_f32_e32 v47, v46, v46
	v_fmamk_f32 v48, v47, 0xbbbac73d, v170
	v_fmaak_f32 v48, v47, v48, 0xbd5c1c4e
	v_fmaak_f32 v48, v47, v48, 0x3e088382
	v_fmaak_f32 v48, v47, v48, 0xbeaaaa99
	v_mul_f32_e64 v48, |v46|, v48
	v_fma_f32 v47, v47, v48, |v46|
	s_or_b64 exec, exec, s[4:5]
	v_fmac_f32_e32 v43, v45, v44
	v_bfi_b32 v45, s2, v47, v46
	v_mul_f32_e32 v42, 0.5, v42
	v_add_f32_e32 v45, 1.0, v45
	v_mul_f32_e32 v42, v42, v45
	v_mul_f32_e32 v42, v43, v42
	v_bfe_u32 v45, v42, 16, 1
	v_or_b32_e32 v46, 0x1800, v12
	v_mov_b32_e32 v47, v13
	s_waitcnt vmcnt(14)
	v_lshlrev_b32_e32 v44, 16, v214
	v_add3_u32 v42, v42, v45, s84
	v_lshl_add_u64 v[46:47], v[82:83], 0, v[46:47]
	global_store_short_d16_hi v[46:47], v42, off
	v_mul_f32_e32 v42, 0x3d372713, v44
	v_mul_f32_e32 v42, v42, v44
	v_fma_f32 v42, v42, v44, v44
	v_mul_f32_e32 v42, 0x3f4c422a, v42
	v_cmp_nlt_f32_e64 s[0:1], |v42|, s80
	s_and_saveexec_b64 s[4:5], s[0:1]
	s_xor_b64 s[4:5], exec, s[4:5]
	s_cbranch_execz .LBB0_385
	v_add_f32_e64 v45, |v42|, |v42|
	v_mul_f32_e32 v46, 0x3fb8aa3b, v45
	v_rndne_f32_e32 v47, v46
	v_sub_f32_e32 v48, v46, v47
	v_fma_f32 v46, v45, s83, -v46
	v_fmac_f32_e32 v46, 0x32a5705f, v45
	v_add_f32_e32 v46, v48, v46
	v_cvt_i32_f32_e32 v47, v47
	v_exp_f32_e32 v46, v46
	v_cmp_ngt_f32_e32 vcc, s76, v45
	v_ldexp_f32 v46, v46, v47
	s_nop 0
	v_cndmask_b32_e32 v46, 0, v46, vcc
	v_cmp_nlt_f32_e32 vcc, s77, v45
	s_nop 1
	v_cndmask_b32_e32 v45, v181, v46, vcc
	v_add_f32_e32 v45, 1.0, v45
	v_rcp_f32_e32 v45, v45
	s_nop 0
	v_fma_f32 v45, v45, -2.0, 1.0
.LBB0_385:
	s_andn2_saveexec_b64 s[4:5], s[4:5]
	v_mul_f32_e32 v45, v42, v42
	v_fmamk_f32 v46, v45, 0xbbbac73d, v170
	v_fmaak_f32 v46, v45, v46, 0xbd5c1c4e
	v_fmaak_f32 v46, v45, v46, 0x3e088382
	v_fmaak_f32 v46, v45, v46, 0xbeaaaa99
	v_mul_f32_e64 v46, |v42|, v46
	v_fma_f32 v45, v45, v46, |v42|
	s_or_b64 exec, exec, s[4:5]
	v_bfi_b32 v42, s2, v45, v42
	v_fma_f32 v40, v40, v43, v38
	v_mul_f32_e32 v43, 0.5, v44
	v_add_f32_e32 v42, 1.0, v42
	v_mul_f32_e32 v42, v43, v42
	v_mul_f32_e32 v42, v40, v42
	v_bfe_u32 v43, v42, 16, 1
	v_add3_u32 v44, v42, v43, s84
	v_or_b32_e32 v42, 0x2000, v12
	v_mov_b32_e32 v43, v13
	s_waitcnt vmcnt(14)
	v_lshlrev_b32_e32 v38, 16, v215
	v_lshl_add_u64 v[42:43], v[82:83], 0, v[42:43]
	global_store_short_d16_hi v[42:43], v44, off
	v_mul_f32_e32 v42, 0x3d372713, v38
	v_mul_f32_e32 v42, v42, v38
	v_fma_f32 v42, v42, v38, v38
	v_mul_f32_e32 v42, 0x3f4c422a, v42
	v_cmp_nlt_f32_e64 s[0:1], |v42|, s80
	s_and_saveexec_b64 s[4:5], s[0:1]
	s_xor_b64 s[4:5], exec, s[4:5]
	s_cbranch_execz .LBB0_389
	v_add_f32_e64 v43, |v42|, |v42|
	v_mul_f32_e32 v44, 0x3fb8aa3b, v43
	v_rndne_f32_e32 v45, v44
	v_sub_f32_e32 v46, v44, v45
	v_fma_f32 v44, v43, s83, -v44
	v_fmac_f32_e32 v44, 0x32a5705f, v43
	v_add_f32_e32 v44, v46, v44
	v_cvt_i32_f32_e32 v45, v45
	v_exp_f32_e32 v44, v44
	v_cmp_ngt_f32_e32 vcc, s76, v43
	v_ldexp_f32 v44, v44, v45
	s_nop 0
	v_cndmask_b32_e32 v44, 0, v44, vcc
	v_cmp_nlt_f32_e32 vcc, s77, v43
	s_nop 1
	v_cndmask_b32_e32 v43, v181, v44, vcc
	v_add_f32_e32 v43, 1.0, v43
	v_rcp_f32_e32 v43, v43
	s_nop 0
	v_fma_f32 v43, v43, -2.0, 1.0
.LBB0_389:
	s_andn2_saveexec_b64 s[4:5], s[4:5]
	v_mul_f32_e32 v43, v42, v42
	v_fmamk_f32 v44, v43, 0xbbbac73d, v170
	v_fmaak_f32 v44, v43, v44, 0xbd5c1c4e
	v_fmaak_f32 v44, v43, v44, 0x3e088382
	v_fmaak_f32 v44, v43, v44, 0xbeaaaa99
	v_mul_f32_e64 v44, |v42|, v44
	v_fma_f32 v43, v43, v44, |v42|
	s_or_b64 exec, exec, s[4:5]
	v_fmac_f32_e32 v39, v41, v40
	v_bfi_b32 v41, s2, v43, v42
	v_mul_f32_e32 v38, 0.5, v38
	v_add_f32_e32 v41, 1.0, v41
	v_mul_f32_e32 v38, v38, v41
	v_mul_f32_e32 v38, v39, v38
	v_bfe_u32 v41, v38, 16, 1
	v_or_b32_e32 v42, 0x2800, v12
	v_mov_b32_e32 v43, v13
	s_waitcnt vmcnt(14)
	v_lshlrev_b32_e32 v40, 16, v216
	v_add3_u32 v38, v38, v41, s84
	v_lshl_add_u64 v[42:43], v[82:83], 0, v[42:43]
	global_store_short_d16_hi v[42:43], v38, off
	v_mul_f32_e32 v38, 0x3d372713, v40
	v_mul_f32_e32 v38, v38, v40
	v_fma_f32 v38, v38, v40, v40
	v_mul_f32_e32 v38, 0x3f4c422a, v38
	v_cmp_nlt_f32_e64 s[0:1], |v38|, s80
	s_and_saveexec_b64 s[4:5], s[0:1]
	s_xor_b64 s[4:5], exec, s[4:5]
	s_cbranch_execz .LBB0_393
	v_add_f32_e64 v41, |v38|, |v38|
	v_mul_f32_e32 v42, 0x3fb8aa3b, v41
	v_rndne_f32_e32 v43, v42
	v_sub_f32_e32 v44, v42, v43
	v_fma_f32 v42, v41, s83, -v42
	v_fmac_f32_e32 v42, 0x32a5705f, v41
	v_add_f32_e32 v42, v44, v42
	v_cvt_i32_f32_e32 v43, v43
	v_exp_f32_e32 v42, v42
	v_cmp_ngt_f32_e32 vcc, s76, v41
	v_ldexp_f32 v42, v42, v43
	s_nop 0
	v_cndmask_b32_e32 v42, 0, v42, vcc
	v_cmp_nlt_f32_e32 vcc, s77, v41
	s_nop 1
	v_cndmask_b32_e32 v41, v181, v42, vcc
	v_add_f32_e32 v41, 1.0, v41
	v_rcp_f32_e32 v41, v41
	s_nop 0
	v_fma_f32 v41, v41, -2.0, 1.0
; __device__ __forceinline__ float bf2f(unsigned v) { return __uint_as_float(v << 16); }
; __device__ __forceinline__ unsigned f2bf(float f) { unsigned u = __float_as_uint(f); return (u + 0x7fffu + ((u >> 16) & 1u)) >> 16; }
; __device__ __forceinline__ float gelu_tanh(float x) { return 0.5f * x * (1.f + tanhf(0.7978845608028654f * (x + 0.044715f * x * x * x))); }
; __device__ __forceinline__ void rg_item(CArgs& A, int l, const bf16* P, bf16* Y, int b, int h, int cg, float* ldsf, int tid) {
;     ...
;             for (int j = 0; j < 16; ++j) gate[j] = bf2f(P[(row0 + j) * NP + PC_RGG + h * 64 + cg * 16 + c]);
; #pragma unroll
;             for (int j = 0; j < 16; ++j) { hv = aa[j] * hv + uu[j]; Y[(row0 + j) * DM + h * 64 + cg * 16 + c] = (bf16)f2bf(hv * gelu_tanh(gate[j])); }
.LBB0_393:
	s_andn2_saveexec_b64 s[4:5], s[4:5]
	v_mul_f32_e32 v41, v38, v38
	v_fmamk_f32 v42, v41, 0xbbbac73d, v170
	v_fmaak_f32 v42, v41, v42, 0xbd5c1c4e
	v_fmaak_f32 v42, v41, v42, 0x3e088382
	v_fmaak_f32 v42, v41, v42, 0xbeaaaa99
	v_mul_f32_e64 v42, |v38|, v42
	v_fma_f32 v41, v41, v42, |v38|
	s_or_b64 exec, exec, s[4:5]
	v_bfi_b32 v38, s2, v41, v38
	v_fma_f32 v36, v36, v39, v34
	v_mul_f32_e32 v39, 0.5, v40
	v_add_f32_e32 v38, 1.0, v38
	v_mul_f32_e32 v38, v39, v38
	v_mul_f32_e32 v38, v36, v38
	v_bfe_u32 v39, v38, 16, 1
	v_add3_u32 v40, v38, v39, s84
	v_or_b32_e32 v38, 0x3000, v12
	v_mov_b32_e32 v39, v13
	s_waitcnt vmcnt(14)
	v_lshlrev_b32_e32 v34, 16, v217
	v_lshl_add_u64 v[38:39], v[82:83], 0, v[38:39]
	global_store_short_d16_hi v[38:39], v40, off
	v_mul_f32_e32 v38, 0x3d372713, v34
	v_mul_f32_e32 v38, v38, v34
	v_fma_f32 v38, v38, v34, v34
	v_mul_f32_e32 v38, 0x3f4c422a, v38
	v_cmp_nlt_f32_e64 s[0:1], |v38|, s80
	s_and_saveexec_b64 s[4:5], s[0:1]
	s_xor_b64 s[4:5], exec, s[4:5]
	s_cbranch_execz .LBB0_397
	v_add_f32_e64 v39, |v38|, |v38|
	v_mul_f32_e32 v40, 0x3fb8aa3b, v39
	v_rndne_f32_e32 v41, v40
	v_sub_f32_e32 v42, v40, v41
	v_fma_f32 v40, v39, s83, -v40
	v_fmac_f32_e32 v40, 0x32a5705f, v39
	v_add_f32_e32 v40, v42, v40
	v_cvt_i32_f32_e32 v41, v41
	v_exp_f32_e32 v40, v40
	v_cmp_ngt_f32_e32 vcc, s76, v39
	v_ldexp_f32 v40, v40, v41
	s_nop 0
	v_cndmask_b32_e32 v40, 0, v40, vcc
	v_cmp_nlt_f32_e32 vcc, s77, v39
	s_nop 1
	v_cndmask_b32_e32 v39, v181, v40, vcc
	v_add_f32_e32 v39, 1.0, v39
	v_rcp_f32_e32 v39, v39
	s_nop 0
	v_fma_f32 v39, v39, -2.0, 1.0
.LBB0_397:
	s_andn2_saveexec_b64 s[4:5], s[4:5]
	v_mul_f32_e32 v39, v38, v38
	v_fmamk_f32 v40, v39, 0xbbbac73d, v170
	v_fmaak_f32 v40, v39, v40, 0xbd5c1c4e
	v_fmaak_f32 v40, v39, v40, 0x3e088382
	v_fmaak_f32 v40, v39, v40, 0xbeaaaa99
	v_mul_f32_e64 v40, |v38|, v40
	v_fma_f32 v39, v39, v40, |v38|
	s_or_b64 exec, exec, s[4:5]
	v_fmac_f32_e32 v35, v37, v36
	v_bfi_b32 v37, s2, v39, v38
	v_mul_f32_e32 v34, 0.5, v34
	v_add_f32_e32 v37, 1.0, v37
	v_mul_f32_e32 v34, v34, v37
	v_mul_f32_e32 v34, v35, v34
	v_bfe_u32 v37, v34, 16, 1
	v_or_b32_e32 v38, 0x3800, v12
	v_mov_b32_e32 v39, v13
	s_waitcnt vmcnt(14)
	v_lshlrev_b32_e32 v36, 16, v218
	v_add3_u32 v34, v34, v37, s84
	v_lshl_add_u64 v[38:39], v[82:83], 0, v[38:39]
	global_store_short_d16_hi v[38:39], v34, off
	v_mul_f32_e32 v34, 0x3d372713, v36
	v_mul_f32_e32 v34, v34, v36
	v_fma_f32 v34, v34, v36, v36
	v_mul_f32_e32 v34, 0x3f4c422a, v34
	v_cmp_nlt_f32_e64 s[0:1], |v34|, s80
	s_and_saveexec_b64 s[4:5], s[0:1]
	s_xor_b64 s[4:5], exec, s[4:5]
	s_cbranch_execz .LBB0_401
	v_add_f32_e64 v37, |v34|, |v34|
	v_mul_f32_e32 v38, 0x3fb8aa3b, v37
	v_rndne_f32_e32 v39, v38
	v_sub_f32_e32 v40, v38, v39
	v_fma_f32 v38, v37, s83, -v38
	v_fmac_f32_e32 v38, 0x32a5705f, v37
	v_add_f32_e32 v38, v40, v38
	v_cvt_i32_f32_e32 v39, v39
	v_exp_f32_e32 v38, v38
	v_cmp_ngt_f32_e32 vcc, s76, v37
	v_ldexp_f32 v38, v38, v39
	s_nop 0
	v_cndmask_b32_e32 v38, 0, v38, vcc
	v_cmp_nlt_f32_e32 vcc, s77, v37
	s_nop 1
	v_cndmask_b32_e32 v37, v181, v38, vcc
	v_add_f32_e32 v37, 1.0, v37
	v_rcp_f32_e32 v37, v37
	s_nop 0
	v_fma_f32 v37, v37, -2.0, 1.0
.LBB0_401:
	s_andn2_saveexec_b64 s[4:5], s[4:5]
	v_mul_f32_e32 v37, v34, v34
	v_fmamk_f32 v38, v37, 0xbbbac73d, v170
	v_fmaak_f32 v38, v37, v38, 0xbd5c1c4e
	v_fmaak_f32 v38, v37, v38, 0x3e088382
	v_fmaak_f32 v38, v37, v38, 0xbeaaaa99
	v_mul_f32_e64 v38, |v34|, v38
	v_fma_f32 v37, v37, v38, |v34|
	s_or_b64 exec, exec, s[4:5]
	v_bfi_b32 v34, s2, v37, v34
	v_fma_f32 v16, v16, v35, v14
	v_mul_f32_e32 v35, 0.5, v36
	v_add_f32_e32 v34, 1.0, v34
	v_mul_f32_e32 v34, v35, v34
	v_mul_f32_e32 v34, v16, v34
	v_bfe_u32 v35, v34, 16, 1
	v_add3_u32 v36, v34, v35, s84
	v_or_b32_e32 v34, 0x4000, v12
	v_mov_b32_e32 v35, v13
	s_waitcnt vmcnt(14)
	v_lshlrev_b32_e32 v14, 16, v219
	v_lshl_add_u64 v[34:35], v[82:83], 0, v[34:35]
	global_store_short_d16_hi v[34:35], v36, off
	v_mul_f32_e32 v34, 0x3d372713, v14
	v_mul_f32_e32 v34, v34, v14
	v_fma_f32 v34, v34, v14, v14
	v_mul_f32_e32 v34, 0x3f4c422a, v34
	v_cmp_nlt_f32_e64 s[0:1], |v34|, s80
	s_and_saveexec_b64 s[4:5], s[0:1]
	s_xor_b64 s[4:5], exec, s[4:5]
	s_cbranch_execz .LBB0_405
	v_add_f32_e64 v35, |v34|, |v34|
	v_mul_f32_e32 v36, 0x3fb8aa3b, v35
	v_rndne_f32_e32 v37, v36
	v_sub_f32_e32 v38, v36, v37
	v_fma_f32 v36, v35, s83, -v36
	v_fmac_f32_e32 v36, 0x32a5705f, v35
	v_add_f32_e32 v36, v38, v36
	v_cvt_i32_f32_e32 v37, v37
	v_exp_f32_e32 v36, v36
	v_cmp_ngt_f32_e32 vcc, s76, v35
	v_ldexp_f32 v36, v36, v37
	s_nop 0
	v_cndmask_b32_e32 v36, 0, v36, vcc
	v_cmp_nlt_f32_e32 vcc, s77, v35
	s_nop 1
	v_cndmask_b32_e32 v35, v181, v36, vcc
	v_add_f32_e32 v35, 1.0, v35
	v_rcp_f32_e32 v35, v35
	s_nop 0
	v_fma_f32 v35, v35, -2.0, 1.0
.LBB0_405:
	s_andn2_saveexec_b64 s[4:5], s[4:5]
	v_mul_f32_e32 v35, v34, v34
	v_fmamk_f32 v36, v35, 0xbbbac73d, v170
	v_fmaak_f32 v36, v35, v36, 0xbd5c1c4e
	v_fmaak_f32 v36, v35, v36, 0x3e088382
	v_fmaak_f32 v36, v35, v36, 0xbeaaaa99
	v_mul_f32_e64 v36, |v34|, v36
	v_fma_f32 v35, v35, v36, |v34|
	s_or_b64 exec, exec, s[4:5]
	v_fmac_f32_e32 v15, v17, v16
	v_bfi_b32 v17, s2, v35, v34
	v_mul_f32_e32 v14, 0.5, v14
	v_add_f32_e32 v17, 1.0, v17
	v_mul_f32_e32 v14, v14, v17
	v_mul_f32_e32 v14, v15, v14
	v_bfe_u32 v17, v14, 16, 1
	v_or_b32_e32 v34, 0x4800, v12
	v_mov_b32_e32 v35, v13
	s_waitcnt vmcnt(14)
	v_lshlrev_b32_e32 v16, 16, v220
	v_add3_u32 v14, v14, v17, s84
	v_lshl_add_u64 v[34:35], v[82:83], 0, v[34:35]
	global_store_short_d16_hi v[34:35], v14, off
	v_mul_f32_e32 v14, 0x3d372713, v16
	v_mul_f32_e32 v14, v14, v16
	v_fma_f32 v14, v14, v16, v16
	v_mul_f32_e32 v14, 0x3f4c422a, v14
	v_cmp_nlt_f32_e64 s[0:1], |v14|, s80
	s_and_saveexec_b64 s[4:5], s[0:1]
	s_xor_b64 s[4:5], exec, s[4:5]
	s_cbranch_execz .LBB0_409
	v_add_f32_e64 v17, |v14|, |v14|
	v_mul_f32_e32 v34, 0x3fb8aa3b, v17
	v_rndne_f32_e32 v35, v34
	v_sub_f32_e32 v36, v34, v35
	v_fma_f32 v34, v17, s83, -v34
	v_fmac_f32_e32 v34, 0x32a5705f, v17
	v_add_f32_e32 v34, v36, v34
	v_cvt_i32_f32_e32 v35, v35
	v_exp_f32_e32 v34, v34
	v_cmp_ngt_f32_e32 vcc, s76, v17
	v_ldexp_f32 v34, v34, v35
	s_nop 0
	v_cndmask_b32_e32 v34, 0, v34, vcc
	v_cmp_nlt_f32_e32 vcc, s77, v17
	s_nop 1
	v_cndmask_b32_e32 v17, v181, v34, vcc
	v_add_f32_e32 v17, 1.0, v17
	v_rcp_f32_e32 v17, v17
	s_nop 0
	v_fma_f32 v17, v17, -2.0, 1.0
; __device__ __forceinline__ float bf2f(unsigned v) { return __uint_as_float(v << 16); }
; __device__ __forceinline__ unsigned f2bf(float f) { unsigned u = __float_as_uint(f); return (u + 0x7fffu + ((u >> 16) & 1u)) >> 16; }
; __device__ __forceinline__ float gelu_tanh(float x) { return 0.5f * x * (1.f + tanhf(0.7978845608028654f * (x + 0.044715f * x * x * x))); }
; __device__ __forceinline__ void rg_item(CArgs& A, int l, const bf16* P, bf16* Y, int b, int h, int cg, float* ldsf, int tid) {
;     ...
;             for (int j = 0; j < 16; ++j) gate[j] = bf2f(P[(row0 + j) * NP + PC_RGG + h * 64 + cg * 16 + c]);
; #pragma unroll
;             for (int j = 0; j < 16; ++j) { hv = aa[j] * hv + uu[j]; Y[(row0 + j) * DM + h * 64 + cg * 16 + c] = (bf16)f2bf(hv * gelu_tanh(gate[j])); }
.LBB0_409:
	s_andn2_saveexec_b64 s[4:5], s[4:5]
	v_mul_f32_e32 v17, v14, v14
	v_fmamk_f32 v34, v17, 0xbbbac73d, v170
	v_fmaak_f32 v34, v17, v34, 0xbd5c1c4e
	v_fmaak_f32 v34, v17, v34, 0x3e088382
	v_fmaak_f32 v34, v17, v34, 0xbeaaaa99
	v_mul_f32_e64 v34, |v14|, v34
	v_fma_f32 v17, v17, v34, |v14|
	s_or_b64 exec, exec, s[4:5]
	v_bfi_b32 v14, s2, v17, v14
	v_fma_f32 v10, v10, v15, v8
	v_mul_f32_e32 v15, 0.5, v16
	v_add_f32_e32 v14, 1.0, v14
	v_mul_f32_e32 v14, v15, v14
	v_mul_f32_e32 v14, v10, v14
	v_bfe_u32 v15, v14, 16, 1
	v_add3_u32 v16, v14, v15, s84
	v_or_b32_e32 v14, 0x5000, v12
	v_mov_b32_e32 v15, v13
	s_waitcnt vmcnt(14)
	v_lshlrev_b32_e32 v8, 16, v221
	v_lshl_add_u64 v[14:15], v[82:83], 0, v[14:15]
	global_store_short_d16_hi v[14:15], v16, off
	v_mul_f32_e32 v14, 0x3d372713, v8
	v_mul_f32_e32 v14, v14, v8
	v_fma_f32 v14, v14, v8, v8
	v_mul_f32_e32 v14, 0x3f4c422a, v14
	v_cmp_nlt_f32_e64 s[0:1], |v14|, s80
	s_and_saveexec_b64 s[4:5], s[0:1]
	s_xor_b64 s[4:5], exec, s[4:5]
	s_cbranch_execz .LBB0_413
	v_add_f32_e64 v15, |v14|, |v14|
	v_mul_f32_e32 v16, 0x3fb8aa3b, v15
	v_rndne_f32_e32 v17, v16
	v_sub_f32_e32 v34, v16, v17
	v_fma_f32 v16, v15, s83, -v16
	v_fmac_f32_e32 v16, 0x32a5705f, v15
	v_add_f32_e32 v16, v34, v16
	v_cvt_i32_f32_e32 v17, v17
	v_exp_f32_e32 v16, v16
	v_cmp_ngt_f32_e32 vcc, s76, v15
	v_ldexp_f32 v16, v16, v17
	s_nop 0
	v_cndmask_b32_e32 v16, 0, v16, vcc
	v_cmp_nlt_f32_e32 vcc, s77, v15
	s_nop 1
	v_cndmask_b32_e32 v15, v181, v16, vcc
	v_add_f32_e32 v15, 1.0, v15
	v_rcp_f32_e32 v15, v15
	s_nop 0
	v_fma_f32 v15, v15, -2.0, 1.0
.LBB0_413:
	s_andn2_saveexec_b64 s[4:5], s[4:5]
	v_mul_f32_e32 v15, v14, v14
	v_fmamk_f32 v16, v15, 0xbbbac73d, v170
	v_fmaak_f32 v16, v15, v16, 0xbd5c1c4e
	v_fmaak_f32 v16, v15, v16, 0x3e088382
	v_fmaak_f32 v16, v15, v16, 0xbeaaaa99
	v_mul_f32_e64 v16, |v14|, v16
	v_fma_f32 v15, v15, v16, |v14|
	s_or_b64 exec, exec, s[4:5]
	v_fmac_f32_e32 v9, v11, v10
	v_bfi_b32 v11, s2, v15, v14
	v_mul_f32_e32 v8, 0.5, v8
	v_add_f32_e32 v11, 1.0, v11
	v_mul_f32_e32 v8, v8, v11
	v_mul_f32_e32 v8, v9, v8
	v_bfe_u32 v11, v8, 16, 1
	v_or_b32_e32 v14, 0x5800, v12
	v_mov_b32_e32 v15, v13
	s_waitcnt vmcnt(14)
	v_lshlrev_b32_e32 v10, 16, v222
	v_add3_u32 v8, v8, v11, s84
	v_lshl_add_u64 v[14:15], v[82:83], 0, v[14:15]
	global_store_short_d16_hi v[14:15], v8, off
	v_mul_f32_e32 v8, 0x3d372713, v10
	v_mul_f32_e32 v8, v8, v10
	v_fma_f32 v8, v8, v10, v10
	v_mul_f32_e32 v8, 0x3f4c422a, v8
	v_cmp_nlt_f32_e64 s[0:1], |v8|, s80
	s_and_saveexec_b64 s[4:5], s[0:1]
	s_xor_b64 s[4:5], exec, s[4:5]
	s_cbranch_execz .LBB0_417
	v_add_f32_e64 v11, |v8|, |v8|
	v_mul_f32_e32 v14, 0x3fb8aa3b, v11
	v_rndne_f32_e32 v15, v14
	v_sub_f32_e32 v16, v14, v15
	v_fma_f32 v14, v11, s83, -v14
	v_fmac_f32_e32 v14, 0x32a5705f, v11
	v_add_f32_e32 v14, v16, v14
	v_cvt_i32_f32_e32 v15, v15
	v_exp_f32_e32 v14, v14
	v_cmp_ngt_f32_e32 vcc, s76, v11
	v_ldexp_f32 v14, v14, v15
	s_nop 0
	v_cndmask_b32_e32 v14, 0, v14, vcc
	v_cmp_nlt_f32_e32 vcc, s77, v11
	s_nop 1
	v_cndmask_b32_e32 v11, v181, v14, vcc
	v_add_f32_e32 v11, 1.0, v11
	v_rcp_f32_e32 v11, v11
	s_nop 0
	v_fma_f32 v11, v11, -2.0, 1.0
; __device__ __forceinline__ float bf2f(unsigned v) { return __uint_as_float(v << 16); }
; __device__ __forceinline__ unsigned f2bf(float f) { unsigned u = __float_as_uint(f); return (u + 0x7fffu + ((u >> 16) & 1u)) >> 16; }
; __device__ __forceinline__ float gelu_tanh(float x) { return 0.5f * x * (1.f + tanhf(0.7978845608028654f * (x + 0.044715f * x * x * x))); }
; __device__ __forceinline__ void rg_item(CArgs& A, int l, const bf16* P, bf16* Y, int b, int h, int cg, float* ldsf, int tid) {
;     ...
;             for (int j = 0; j < 16; ++j) gate[j] = bf2f(P[(row0 + j) * NP + PC_RGG + h * 64 + cg * 16 + c]);
; #pragma unroll
;             for (int j = 0; j < 16; ++j) { hv = aa[j] * hv + uu[j]; Y[(row0 + j) * DM + h * 64 + cg * 16 + c] = (bf16)f2bf(hv * gelu_tanh(gate[j])); }
.LBB0_417:
	s_andn2_saveexec_b64 s[4:5], s[4:5]
	v_mul_f32_e32 v11, v8, v8
	v_fmamk_f32 v14, v11, 0xbbbac73d, v170
	v_fmaak_f32 v14, v11, v14, 0xbd5c1c4e
	v_fmaak_f32 v14, v11, v14, 0x3e088382
	v_fmaak_f32 v14, v11, v14, 0xbeaaaa99
	v_mul_f32_e64 v14, |v8|, v14
	v_fma_f32 v11, v11, v14, |v8|
	s_or_b64 exec, exec, s[4:5]
	v_bfi_b32 v8, s2, v11, v8
	v_fma_f32 v6, v6, v9, v4
	v_mul_f32_e32 v9, 0.5, v10
	v_add_f32_e32 v8, 1.0, v8
	v_mul_f32_e32 v8, v9, v8
	v_mul_f32_e32 v8, v6, v8
	v_bfe_u32 v9, v8, 16, 1
	v_add3_u32 v10, v8, v9, s84
	v_or_b32_e32 v8, 0x6000, v12
	v_mov_b32_e32 v9, v13
	s_waitcnt vmcnt(14)
	v_lshlrev_b32_e32 v4, 16, v223
	v_lshl_add_u64 v[8:9], v[82:83], 0, v[8:9]
	global_store_short_d16_hi v[8:9], v10, off
	v_mul_f32_e32 v8, 0x3d372713, v4
	v_mul_f32_e32 v8, v8, v4
	v_fma_f32 v8, v8, v4, v4
	v_mul_f32_e32 v8, 0x3f4c422a, v8
	v_cmp_nlt_f32_e64 s[0:1], |v8|, s80
	s_and_saveexec_b64 s[4:5], s[0:1]
	s_xor_b64 s[4:5], exec, s[4:5]
	s_cbranch_execz .LBB0_421
	v_add_f32_e64 v9, |v8|, |v8|
	v_mul_f32_e32 v10, 0x3fb8aa3b, v9
	v_rndne_f32_e32 v11, v10
	v_sub_f32_e32 v14, v10, v11
	v_fma_f32 v10, v9, s83, -v10
	v_fmac_f32_e32 v10, 0x32a5705f, v9
	v_add_f32_e32 v10, v14, v10
	v_cvt_i32_f32_e32 v11, v11
	v_exp_f32_e32 v10, v10
	v_cmp_ngt_f32_e32 vcc, s76, v9
	v_ldexp_f32 v10, v10, v11
	s_nop 0
	v_cndmask_b32_e32 v10, 0, v10, vcc
	v_cmp_nlt_f32_e32 vcc, s77, v9
	s_nop 1
	v_cndmask_b32_e32 v9, v181, v10, vcc
	v_add_f32_e32 v9, 1.0, v9
	v_rcp_f32_e32 v9, v9
	s_nop 0
	v_fma_f32 v9, v9, -2.0, 1.0
.LBB0_421:
	s_andn2_saveexec_b64 s[4:5], s[4:5]
	v_mul_f32_e32 v9, v8, v8
	v_fmamk_f32 v10, v9, 0xbbbac73d, v170
	v_fmaak_f32 v10, v9, v10, 0xbd5c1c4e
	v_fmaak_f32 v10, v9, v10, 0x3e088382
	v_fmaak_f32 v10, v9, v10, 0xbeaaaa99
	v_mul_f32_e64 v10, |v8|, v10
	v_fma_f32 v9, v9, v10, |v8|
	s_or_b64 exec, exec, s[4:5]
	v_fmac_f32_e32 v5, v7, v6
	v_bfi_b32 v7, s2, v9, v8
	v_mul_f32_e32 v4, 0.5, v4
	v_add_f32_e32 v7, 1.0, v7
	v_mul_f32_e32 v4, v4, v7
	v_mul_f32_e32 v4, v5, v4
	v_bfe_u32 v7, v4, 16, 1
	v_or_b32_e32 v8, 0x6800, v12
	v_mov_b32_e32 v9, v13
	s_waitcnt vmcnt(14)
	v_lshlrev_b32_e32 v6, 16, v224
	v_add3_u32 v4, v4, v7, s84
	v_lshl_add_u64 v[8:9], v[82:83], 0, v[8:9]
	global_store_short_d16_hi v[8:9], v4, off
	v_mul_f32_e32 v4, 0x3d372713, v6
	v_mul_f32_e32 v4, v4, v6
	v_fma_f32 v4, v4, v6, v6
	v_mul_f32_e32 v7, 0x3f4c422a, v4
	v_cmp_nlt_f32_e64 s[0:1], |v7|, s80
	s_and_saveexec_b64 s[4:5], s[0:1]
	s_xor_b64 s[4:5], exec, s[4:5]
	s_cbranch_execz .LBB0_425
	v_add_f32_e64 v4, |v7|, |v7|
	v_mul_f32_e32 v8, 0x3fb8aa3b, v4
	v_rndne_f32_e32 v9, v8
	v_sub_f32_e32 v10, v8, v9
	v_fma_f32 v8, v4, s83, -v8
	v_fmac_f32_e32 v8, 0x32a5705f, v4
	v_add_f32_e32 v8, v10, v8
	v_cvt_i32_f32_e32 v9, v9
	v_exp_f32_e32 v8, v8
	v_cmp_ngt_f32_e32 vcc, s76, v4
	v_ldexp_f32 v8, v8, v9
	s_nop 0
	v_cndmask_b32_e32 v8, 0, v8, vcc
	v_cmp_nlt_f32_e32 vcc, s77, v4
	s_nop 1
	v_cndmask_b32_e32 v4, v181, v8, vcc
	v_add_f32_e32 v4, 1.0, v4
	v_rcp_f32_e32 v4, v4
	s_nop 0
	v_fma_f32 v8, v4, -2.0, 1.0
.LBB0_425:
	s_andn2_saveexec_b64 s[4:5], s[4:5]
	v_mul_f32_e32 v4, v7, v7
	v_fmamk_f32 v8, v4, 0xbbbac73d, v170
	v_fmaak_f32 v8, v4, v8, 0xbd5c1c4e
	v_fmaak_f32 v8, v4, v8, 0x3e088382
	v_fmaak_f32 v8, v4, v8, 0xbeaaaa99
	v_mul_f32_e64 v8, |v7|, v8
	v_fma_f32 v8, v4, v8, |v7|
	s_or_b64 exec, exec, s[4:5]
	v_fmac_f32_e32 v50, v51, v5
	v_mul_f32_e32 v5, 0.5, v6
	v_bfi_b32 v6, s2, v8, v7
	v_add_f32_e32 v6, 1.0, v6
	v_mul_f32_e32 v5, v5, v6
	v_mul_f32_e32 v5, v50, v5
	v_bfe_u32 v6, v5, 16, 1
	v_add3_u32 v5, v5, v6, s84
	v_or_b32_e32 v6, 0x7000, v12
	v_mov_b32_e32 v7, v13
	s_waitcnt vmcnt(14)
	v_lshlrev_b32_e32 v4, 16, v225
	v_lshl_add_u64 v[6:7], v[82:83], 0, v[6:7]
	global_store_short_d16_hi v[6:7], v5, off
	v_mul_f32_e32 v5, 0x3d372713, v4
	v_mul_f32_e32 v5, v5, v4
	v_fma_f32 v5, v5, v4, v4
	v_mul_f32_e32 v5, 0x3f4c422a, v5
	v_cmp_nlt_f32_e64 s[0:1], |v5|, s80
	s_and_saveexec_b64 s[4:5], s[0:1]
	s_xor_b64 s[4:5], exec, s[4:5]
	s_cbranch_execz .LBB0_429
	v_add_f32_e64 v6, |v5|, |v5|
	v_mul_f32_e32 v7, 0x3fb8aa3b, v6
	v_rndne_f32_e32 v8, v7
	v_sub_f32_e32 v9, v7, v8
	v_fma_f32 v7, v6, s83, -v7
	v_fmac_f32_e32 v7, 0x32a5705f, v6
	v_add_f32_e32 v7, v9, v7
	v_cvt_i32_f32_e32 v8, v8
	v_exp_f32_e32 v7, v7
	v_cmp_ngt_f32_e32 vcc, s76, v6
	v_ldexp_f32 v7, v7, v8
	s_nop 0
	v_cndmask_b32_e32 v7, 0, v7, vcc
	v_cmp_nlt_f32_e32 vcc, s77, v6
	s_nop 1
	v_cndmask_b32_e32 v6, v181, v7, vcc
	v_add_f32_e32 v6, 1.0, v6
	v_rcp_f32_e32 v6, v6
	s_nop 0
	v_fma_f32 v6, v6, -2.0, 1.0
